# phase-0 filter MLP: weight loads re-emitted as rolling prefetch (16-18 loads in flight) instead of load-wait-mfma one at a time
# speedup vs baseline: 1.0061x; 1.0061x over previous
; __device__ __forceinline__ int crow16(int r, int hi) { return (r & 3) + 8 * (r >> 2) + 4 * hi; }
; __device__ __forceinline__ void filter_item32(const Args& a, int L, bf16* KR, int t0, int np0, int npn, int lane) {
;     ...
;     for (int layer = 0; layer < 2; ++layer) {
;         const float* W = layer ? w3 : w2; const float* bb = layer ? b3 : b2;
;         f32x16 g0 = {}, g1 = {}; const int lo2 = 4 * hi * 64 + n;
; #pragma unroll
;         for (int kk = 0; kk < 32; ++kk) {
;             const float* ub = W + (32 * (kk >> 4) + crow16(kk & 15, 0)) * 64;
;             const float zb = kk < 16 ? h0[kk & 15] : h1[kk & 15];
;             const float a0 = ub[lo2], a1 = ub[lo2 + 32];
;             g0 = __builtin_amdgcn_mfma_f32_32x32x2f32(a0, zb, g0, 0, 0, 0); g1 = __builtin_amdgcn_mfma_f32_32x32x2f32(a1, zb, g1, 0, 0, 0);
;         }
.LBB0_185:
	s_and_b64 s[2:3], s[8:9], exec
	s_cselect_b32 s3, s77, s81
	s_cselect_b32 s2, s76, s80
	v_lshlrev_b32_e32 v80, 2, v108
	s_cselect_b32 s11, s79, s83
	s_cselect_b32 s10, s78, s82
	v_mov_b32_e32 v252, v80
	v_add_u32_e32 v253, 0x1000, v80
	v_add_u32_e32 v254, 0x2000, v80
	v_add_u32_e32 v255, 0x3000, v80
	global_load_dword v234, v252, s[2:3]
	global_load_dword v235, v252, s[2:3] offset:256
	global_load_dword v236, v252, s[2:3] offset:128
	global_load_dword v237, v252, s[2:3] offset:384
	global_load_dword v238, v252, s[2:3] offset:512
	global_load_dword v239, v252, s[2:3] offset:640
	global_load_dword v240, v252, s[2:3] offset:768
	global_load_dword v241, v252, s[2:3] offset:896
	global_load_dword v244, v252, s[2:3] offset:2048
	global_load_dword v245, v252, s[2:3] offset:2176
	global_load_dword v246, v252, s[2:3] offset:2304
	global_load_dword v247, v252, s[2:3] offset:2432
	global_load_dword v248, v252, s[2:3] offset:2560
	global_load_dword v249, v252, s[2:3] offset:2688
	global_load_dword v250, v252, s[2:3] offset:2816
	global_load_dword v251, v252, s[2:3] offset:2944
	s_waitcnt vmcnt(15)
	v_mfma_f32_32x32x2_f32 v[18:33], v234, v2, 0
	global_load_dword v234, v253, s[2:3]
	s_waitcnt vmcnt(15)
	v_mfma_f32_32x32x2_f32 v[18:33], v235, v1, v[18:33]
	global_load_dword v235, v253, s[2:3] offset:128
	s_waitcnt vmcnt(15)
	v_mfma_f32_32x32x2_f32 v[2:17], v236, v2, 0
	global_load_dword v236, v253, s[2:3] offset:256
	s_waitcnt vmcnt(15)
	v_mfma_f32_32x32x2_f32 v[2:17], v237, v1, v[2:17]
	global_load_dword v237, v253, s[2:3] offset:384
	s_waitcnt vmcnt(15)
	v_mfma_f32_32x32x2_f32 v[18:33], v238, v34, v[18:33]
	global_load_dword v238, v253, s[2:3] offset:512
	s_waitcnt vmcnt(15)
	v_mfma_f32_32x32x2_f32 v[2:17], v239, v34, v[2:17]
	global_load_dword v239, v253, s[2:3] offset:640
	s_waitcnt vmcnt(15)
	v_mfma_f32_32x32x2_f32 v[18:33], v240, v35, v[18:33]
	global_load_dword v240, v253, s[2:3] offset:768
	s_waitcnt vmcnt(15)
	v_mfma_f32_32x32x2_f32 v[2:17], v241, v35, v[2:17]
	global_load_dword v241, v253, s[2:3] offset:896
	s_waitcnt vmcnt(15)
	v_mfma_f32_32x32x2_f32 v[18:33], v244, v36, v[18:33]
	global_load_dword v244, v253, s[2:3] offset:2048
	s_waitcnt vmcnt(15)
	v_mfma_f32_32x32x2_f32 v[2:17], v245, v36, v[2:17]
	global_load_dword v245, v253, s[2:3] offset:2176
	s_waitcnt vmcnt(15)
	v_mfma_f32_32x32x2_f32 v[18:33], v246, v37, v[18:33]
	global_load_dword v246, v253, s[2:3] offset:2304
	s_waitcnt vmcnt(15)
	v_mfma_f32_32x32x2_f32 v[2:17], v247, v37, v[2:17]
	global_load_dword v247, v253, s[2:3] offset:2432
	s_waitcnt vmcnt(15)
	v_mfma_f32_32x32x2_f32 v[18:33], v248, v38, v[18:33]
	global_load_dword v248, v253, s[2:3] offset:2560
	s_waitcnt vmcnt(15)
	v_mfma_f32_32x32x2_f32 v[2:17], v249, v38, v[2:17]
	global_load_dword v249, v253, s[2:3] offset:2688
	s_waitcnt vmcnt(15)
	v_mfma_f32_32x32x2_f32 v[18:33], v250, v39, v[18:33]
	global_load_dword v250, v253, s[2:3] offset:2816
	s_waitcnt vmcnt(15)
	v_mfma_f32_32x32x2_f32 v[2:17], v251, v39, v[2:17]
	global_load_dword v251, v253, s[2:3] offset:2944
	s_waitcnt vmcnt(15)
	v_mfma_f32_32x32x2_f32 v[18:33], v234, v40, v[18:33]
	global_load_dword v234, v254, s[2:3]
	s_waitcnt vmcnt(15)
	v_mfma_f32_32x32x2_f32 v[2:17], v235, v40, v[2:17]
	global_load_dword v235, v254, s[2:3] offset:128
	s_waitcnt vmcnt(15)
	v_mfma_f32_32x32x2_f32 v[18:33], v236, v41, v[18:33]
	global_load_dword v236, v254, s[2:3] offset:256
	s_waitcnt vmcnt(15)
	v_mfma_f32_32x32x2_f32 v[2:17], v237, v41, v[2:17]
	global_load_dword v237, v254, s[2:3] offset:384
	s_waitcnt vmcnt(15)
	v_mfma_f32_32x32x2_f32 v[18:33], v238, v42, v[18:33]
	global_load_dword v238, v254, s[2:3] offset:512
	s_waitcnt vmcnt(15)
	v_mfma_f32_32x32x2_f32 v[2:17], v239, v42, v[2:17]
	global_load_dword v239, v254, s[2:3] offset:640
	s_waitcnt vmcnt(15)
	v_mfma_f32_32x32x2_f32 v[18:33], v240, v43, v[18:33]
	global_load_dword v240, v254, s[2:3] offset:768
	s_waitcnt vmcnt(15)
	v_mfma_f32_32x32x2_f32 v[2:17], v241, v43, v[2:17]
	global_load_dword v241, v254, s[2:3] offset:896
	s_waitcnt vmcnt(15)
	v_mfma_f32_32x32x2_f32 v[18:33], v244, v44, v[18:33]
	global_load_dword v244, v254, s[2:3] offset:2048
	s_waitcnt vmcnt(15)
	v_mfma_f32_32x32x2_f32 v[2:17], v245, v44, v[2:17]
	global_load_dword v245, v254, s[2:3] offset:2176
	s_waitcnt vmcnt(15)
	v_mfma_f32_32x32x2_f32 v[18:33], v246, v45, v[18:33]
	global_load_dword v246, v254, s[2:3] offset:2304
	s_waitcnt vmcnt(15)
	v_mfma_f32_32x32x2_f32 v[2:17], v247, v45, v[2:17]
	global_load_dword v247, v254, s[2:3] offset:2432
	s_waitcnt vmcnt(15)
	v_mfma_f32_32x32x2_f32 v[18:33], v248, v46, v[18:33]
	global_load_dword v248, v254, s[2:3] offset:2560
	s_waitcnt vmcnt(15)
	v_mfma_f32_32x32x2_f32 v[2:17], v249, v46, v[2:17]
	global_load_dword v249, v254, s[2:3] offset:2688
	s_waitcnt vmcnt(15)
	v_mfma_f32_32x32x2_f32 v[18:33], v250, v47, v[18:33]
	global_load_dword v250, v254, s[2:3] offset:2816
	s_waitcnt vmcnt(15)
	v_mfma_f32_32x32x2_f32 v[2:17], v251, v47, v[2:17]
	global_load_dword v251, v254, s[2:3] offset:2944
	s_waitcnt vmcnt(15)
	v_mfma_f32_32x32x2_f32 v[18:33], v234, v48, v[18:33]
	global_load_dword v234, v255, s[2:3]
	s_waitcnt vmcnt(15)
	v_mfma_f32_32x32x2_f32 v[2:17], v235, v48, v[2:17]
	global_load_dword v235, v255, s[2:3] offset:128
	s_waitcnt vmcnt(15)
	v_mfma_f32_32x32x2_f32 v[18:33], v236, v49, v[18:33]
	global_load_dword v236, v255, s[2:3] offset:256
	s_waitcnt vmcnt(15)
	v_mfma_f32_32x32x2_f32 v[2:17], v237, v49, v[2:17]
	global_load_dword v237, v255, s[2:3] offset:384
	s_waitcnt vmcnt(15)
	v_mfma_f32_32x32x2_f32 v[18:33], v238, v50, v[18:33]
	global_load_dword v238, v255, s[2:3] offset:512
	s_waitcnt vmcnt(15)
; __device__ __forceinline__ int crow16(int r, int hi) { return (r & 3) + 8 * (r >> 2) + 4 * hi; }
; __device__ __forceinline__ void filter_item32(const Args& a, int L, bf16* KR, int t0, int np0, int npn, int lane) {
;     ...
;         for (int kk = 0; kk < 32; ++kk) {
;             const float* ub = W + (32 * (kk >> 4) + crow16(kk & 15, 0)) * 64;
;             const float zb = kk < 16 ? h0[kk & 15] : h1[kk & 15];
;             const float a0 = ub[lo2], a1 = ub[lo2 + 32];
;             g0 = __builtin_amdgcn_mfma_f32_32x32x2f32(a0, zb, g0, 0, 0, 0); g1 = __builtin_amdgcn_mfma_f32_32x32x2f32(a1, zb, g1, 0, 0, 0);
;         }
; #pragma unroll
;         for (int r = 0; r < 16; ++r) { const int j = crow16(r, hi); h0[r] = sinf(fq[j] * (g0[r] + bb[j])); h1[r] = sinf(fq[32 + j] * (g1[r] + bb[32 + j])); }
	v_mfma_f32_32x32x2_f32 v[2:17], v239, v50, v[2:17]
	global_load_dword v239, v255, s[2:3] offset:640
	s_waitcnt vmcnt(15)
	v_mfma_f32_32x32x2_f32 v[18:33], v240, v53, v[18:33]
	global_load_dword v240, v255, s[2:3] offset:768
	s_waitcnt vmcnt(15)
	v_mfma_f32_32x32x2_f32 v[2:17], v241, v53, v[2:17]
	global_load_dword v241, v255, s[2:3] offset:896
	s_waitcnt vmcnt(15)
	v_mfma_f32_32x32x2_f32 v[18:33], v244, v54, v[18:33]
	global_load_dword v244, v255, s[2:3] offset:2048
	s_waitcnt vmcnt(15)
	v_mfma_f32_32x32x2_f32 v[2:17], v245, v54, v[2:17]
	global_load_dword v245, v255, s[2:3] offset:2176
	s_waitcnt vmcnt(15)
	v_mfma_f32_32x32x2_f32 v[18:33], v246, v57, v[18:33]
	global_load_dword v246, v255, s[2:3] offset:2304
	s_waitcnt vmcnt(15)
	v_mfma_f32_32x32x2_f32 v[2:17], v247, v57, v[2:17]
	global_load_dword v247, v255, s[2:3] offset:2432
	s_waitcnt vmcnt(15)
	v_mfma_f32_32x32x2_f32 v[18:33], v248, v58, v[18:33]
	global_load_dword v248, v255, s[2:3] offset:2560
	s_waitcnt vmcnt(15)
	v_mfma_f32_32x32x2_f32 v[2:17], v249, v58, v[2:17]
	global_load_dword v249, v255, s[2:3] offset:2688
	s_waitcnt vmcnt(15)
	v_mfma_f32_32x32x2_f32 v[18:33], v250, v61, v[18:33]
	global_load_dword v250, v255, s[2:3] offset:2816
	s_waitcnt vmcnt(15)
	v_mfma_f32_32x32x2_f32 v[2:17], v251, v61, v[2:17]
	global_load_dword v251, v255, s[2:3] offset:2944
	s_waitcnt vmcnt(15)
	v_mfma_f32_32x32x2_f32 v[18:33], v234, v52, v[18:33]
	s_waitcnt vmcnt(14)
	v_mfma_f32_32x32x2_f32 v[2:17], v235, v52, v[2:17]
	s_waitcnt vmcnt(13)
	v_mfma_f32_32x32x2_f32 v[18:33], v236, v55, v[18:33]
	s_waitcnt vmcnt(12)
	v_mfma_f32_32x32x2_f32 v[2:17], v237, v55, v[2:17]
	s_waitcnt vmcnt(11)
	v_mfma_f32_32x32x2_f32 v[18:33], v238, v56, v[18:33]
	s_waitcnt vmcnt(10)
	v_mfma_f32_32x32x2_f32 v[2:17], v239, v56, v[2:17]
	s_waitcnt vmcnt(9)
	v_mfma_f32_32x32x2_f32 v[18:33], v240, v59, v[18:33]
	s_waitcnt vmcnt(8)
	v_mfma_f32_32x32x2_f32 v[2:17], v241, v59, v[2:17]
	s_waitcnt vmcnt(7)
	v_mfma_f32_32x32x2_f32 v[18:33], v244, v60, v[18:33]
	s_waitcnt vmcnt(6)
	v_mfma_f32_32x32x2_f32 v[2:17], v245, v60, v[2:17]
	s_waitcnt vmcnt(5)
	v_mfma_f32_32x32x2_f32 v[18:33], v246, v63, v[18:33]
	s_waitcnt vmcnt(4)
	v_mfma_f32_32x32x2_f32 v[2:17], v247, v63, v[2:17]
	s_waitcnt vmcnt(3)
	v_mfma_f32_32x32x2_f32 v[18:33], v248, v62, v[18:33]
	s_waitcnt vmcnt(2)
	v_mfma_f32_32x32x2_f32 v[2:17], v249, v62, v[2:17]
	s_waitcnt vmcnt(1)
	v_mfma_f32_32x32x2_f32 v[18:33], v250, v51, v[18:33]
	v_lshl_add_u64 v[34:35], s[2:3], 0, v[80:81]
	v_add_co_u32_e32 v36, vcc, s56, v34
	v_addc_co_u32_e32 v37, vcc, 0, v35, vcc
	v_add_co_u32_e32 v38, vcc, s97, v34
	v_lshlrev_b32_e32 v80, 2, v102
	v_addc_co_u32_e32 v39, vcc, 0, v35, vcc
	v_add_co_u32_e32 v34, vcc, s57, v34
	v_addc_co_u32_e32 v35, vcc, 0, v35, vcc
	global_load_dword v1, v80, s[10:11]
	s_waitcnt vmcnt(0)
	s_nop 15
	v_add_f32_e32 v1, v18, v1
	v_mfma_f32_32x32x2_f32 v[2:17], v251, v51, v[2:17]
	v_mul_f32_e32 v1, v65, v1
	v_and_b32_e32 v36, 0x7fffffff, v1
	v_cmp_nlt_f32_e64 s[2:3], |v1|, s60
	s_and_saveexec_b64 s[4:5], s[2:3]
	s_xor_b64 s[12:13], exec, s[4:5]
	s_cbranch_execz .LBB0_187
	v_lshrrev_b32_e32 v18, 23, v36
	v_add_u32_e32 v18, 0xffffff88, v18
	v_cmp_lt_u32_e32 vcc, 63, v18
	v_mov_b32_e32 v39, v81
	v_mov_b32_e32 v41, v81
	v_cndmask_b32_e32 v34, 0, v145, vcc
	v_add_u32_e32 v18, v34, v18
	v_cmp_lt_u32_e64 s[2:3], 31, v18
	v_mov_b32_e32 v43, v81
	v_mov_b32_e32 v45, v81
	v_cndmask_b32_e64 v34, 0, v146, s[2:3]
	v_add_u32_e32 v18, v34, v18
	v_cmp_lt_u32_e64 s[4:5], 31, v18
	v_mov_b32_e32 v47, v81
	v_mov_b32_e32 v49, v81
	v_cndmask_b32_e64 v34, 0, v146, s[4:5]
	v_add_u32_e32 v18, v34, v18
	v_and_b32_e32 v34, 0x7fffff, v36
	v_or_b32_e32 v37, 0x800000, v34
	v_mad_u64_u32 v[34:35], s[6:7], v37, s61, 0
	v_mov_b32_e32 v38, v35
	v_mad_u64_u32 v[38:39], s[6:7], v37, s62, v[38:39]
	v_mov_b32_e32 v40, v39
	v_mad_u64_u32 v[40:41], s[6:7], v37, s63, v[40:41]
	v_mov_b32_e32 v42, v41
	v_mad_u64_u32 v[42:43], s[6:7], v37, s72, v[42:43]
	v_mov_b32_e32 v44, v43
	v_mad_u64_u32 v[44:45], s[6:7], v37, s73, v[44:45]
	v_mov_b32_e32 v46, v45
	v_mad_u64_u32 v[46:47], s[6:7], v37, s74, v[46:47]
	v_mov_b32_e32 v48, v47
	v_mad_u64_u32 v[48:49], s[6:7], v37, s75, v[48:49]
	v_cndmask_b32_e32 v35, v46, v42, vcc
	v_cndmask_b32_e32 v37, v48, v44, vcc
	v_cndmask_b32_e32 v41, v49, v46, vcc
	v_cndmask_b32_e64 v39, v37, v35, s[2:3]
	v_cndmask_b32_e64 v37, v41, v37, s[2:3]
	v_cndmask_b32_e32 v41, v44, v40, vcc
	v_cndmask_b32_e64 v35, v35, v41, s[2:3]
	v_cndmask_b32_e64 v37, v37, v39, s[4:5]
	v_cndmask_b32_e64 v39, v39, v35, s[4:5]
	v_sub_u32_e32 v43, 32, v18
	v_alignbit_b32 v44, v37, v39, v43
	v_cmp_eq_u32_e64 s[6:7], 0, v18
	v_cndmask_b32_e32 v34, v40, v34, vcc
	s_nop 0
	v_cndmask_b32_e64 v18, v44, v37, s[6:7]
	v_cndmask_b32_e32 v37, v42, v38, vcc
	v_cndmask_b32_e64 v38, v41, v37, s[2:3]
	v_cndmask_b32_e64 v35, v35, v38, s[4:5]
	v_alignbit_b32 v41, v39, v35, v43
	v_cndmask_b32_e64 v39, v41, v39, s[6:7]
	v_bfe_u32 v44, v18, 29, 1
	v_cndmask_b32_e64 v34, v37, v34, s[2:3]
	v_alignbit_b32 v41, v18, v39, 30
	v_sub_u32_e32 v45, 0, v44
	v_cndmask_b32_e64 v34, v38, v34, s[4:5]
	v_xor_b32_e32 v41, v41, v45
	v_alignbit_b32 v37, v35, v34, v43
	v_cndmask_b32_e64 v35, v37, v35, s[6:7]
	v_ffbh_u32_e32 v38, v41
	v_alignbit_b32 v37, v39, v35, 30
	v_min_u32_e32 v38, 32, v38
	v_alignbit_b32 v34, v35, v34, 30
	v_xor_b32_e32 v37, v37, v45
	v_sub_u32_e32 v39, 31, v38
	v_xor_b32_e32 v34, v34, v45
	v_alignbit_b32 v40, v41, v37, v39
	v_alignbit_b32 v34, v37, v34, v39
	v_alignbit_b32 v35, v40, v34, 9
	v_ffbh_u32_e32 v37, v35
	v_min_u32_e32 v37, 32, v37
	v_lshrrev_b32_e32 v42, 29, v18
	v_not_b32_e32 v39, v37
	v_alignbit_b32 v34, v35, v34, v39
	v_lshlrev_b32_e32 v35, 31, v42
	v_or_b32_e32 v39, 0x33000000, v35
	v_add_lshl_u32 v37, v37, v38, 23
	v_lshrrev_b32_e32 v34, 9, v34
	v_sub_u32_e32 v37, v39, v37
	v_or_b32_e32 v35, 0.5, v35
	v_lshlrev_b32_e32 v38, 23, v38
	v_or_b32_e32 v34, v37, v34
	v_lshrrev_b32_e32 v37, 9, v40
	v_sub_u32_e32 v35, v35, v38
	v_or_b32_e32 v35, v37, v35
	v_mul_f32_e32 v37, 0x3fc90fda, v35
	v_fma_f32 v38, v35, s0, -v37
	v_fmac_f32_e32 v38, 0x33a22168, v35
	v_fmac_f32_e32 v38, 0x3fc90fda, v34
	v_lshrrev_b32_e32 v18, 30, v18
	v_add_f32_e32 v38, v37, v38
	v_add_u32_e32 v37, v44, v18

; __device__ __forceinline__ int crow16(int r, int hi) { return (r & 3) + 8 * (r >> 2) + 4 * hi; }
; __device__ __forceinline__ void filter_item32(const Args& a, int L, bf16* KR, int t0, int np0, int npn, int lane) {
;     ...
;     for (int np = np0; np < np0 + npn; ++np) {
;         f32x16 of = {}, ob = {};
;         const float* wr = w4 + 32 * np; const int lo4 = 4 * hi * 1024 + n;
; #pragma unroll
;         for (int kk = 0; kk < 32; ++kk) {
;             const float* ub = wr + (32 * (kk >> 4) + crow16(kk & 15, 0)) * 1024;
;             const float zb = kk < 16 ? h0[kk & 15] : h1[kk & 15];
;             const float af = ub[lo4], ab = ub[lo4 + 512];
;             of = __builtin_amdgcn_mfma_f32_32x32x2f32(af, zb, of, 0, 0, 0); ob = __builtin_amdgcn_mfma_f32_32x32x2f32(ab, zb, ob, 0, 0, 0);
;         }
.LBB0_315:
	global_load_dword v234, v[120:121], off
	global_load_dword v235, v[120:121], off offset:2048
	v_add_co_u32_e32 v254, vcc, 0x1000, v120
	s_nop 1
	v_addc_co_u32_e32 v255, vcc, 0, v121, vcc
	global_load_dword v236, v[254:255], off
	global_load_dword v237, v[254:255], off offset:2048
	v_add_co_u32_e32 v254, vcc, 0x2000, v120
	s_nop 1
	v_addc_co_u32_e32 v255, vcc, 0, v121, vcc
	global_load_dword v238, v[254:255], off
	global_load_dword v239, v[254:255], off offset:2048
	v_add_co_u32_e32 v254, vcc, 0x3000, v120
	s_nop 1
	v_addc_co_u32_e32 v255, vcc, 0, v121, vcc
	global_load_dword v240, v[254:255], off
	global_load_dword v241, v[254:255], off offset:2048
	v_add_co_u32_e32 v254, vcc, 0x8000, v120
	s_nop 1
	v_addc_co_u32_e32 v255, vcc, 0, v121, vcc
	global_load_dword v244, v[254:255], off
	global_load_dword v245, v[254:255], off offset:2048
	v_add_co_u32_e32 v254, vcc, 0x9000, v120
	s_nop 1
	v_addc_co_u32_e32 v255, vcc, 0, v121, vcc
	global_load_dword v246, v[254:255], off
	global_load_dword v247, v[254:255], off offset:2048
	v_add_co_u32_e32 v254, vcc, 0xa000, v120
	s_nop 1
	v_addc_co_u32_e32 v255, vcc, 0, v121, vcc
	global_load_dword v248, v[254:255], off
	global_load_dword v249, v[254:255], off offset:2048
	v_add_co_u32_e32 v254, vcc, 0xb000, v120
	s_nop 1
	v_addc_co_u32_e32 v255, vcc, 0, v121, vcc
	global_load_dword v250, v[254:255], off
	global_load_dword v251, v[254:255], off offset:2048
	v_add_co_u32_e32 v254, vcc, 0x10000, v120
	s_nop 1
	v_addc_co_u32_e32 v255, vcc, 0, v121, vcc
	global_load_dword v252, v[254:255], off
	global_load_dword v253, v[254:255], off offset:2048
	s_waitcnt vmcnt(16)
	v_mfma_f32_32x32x2_f32 v[64:79], v234, v2, 0
	v_mfma_f32_32x32x2_f32 v[4:19], v235, v2, 0
	v_add_co_u32_e32 v254, vcc, 0x11000, v120
	s_nop 1
	v_addc_co_u32_e32 v255, vcc, 0, v121, vcc
	global_load_dword v234, v[254:255], off
	global_load_dword v235, v[254:255], off offset:2048
	s_waitcnt vmcnt(16)
	v_mfma_f32_32x32x2_f32 v[4:19], v237, v1, v[4:19]
	v_mfma_f32_32x32x2_f32 v[64:79], v236, v1, v[64:79]
	v_add_co_u32_e32 v254, vcc, 0x12000, v120
	s_nop 1
	v_addc_co_u32_e32 v255, vcc, 0, v121, vcc
	global_load_dword v236, v[254:255], off
	global_load_dword v237, v[254:255], off offset:2048
	s_waitcnt vmcnt(16)
	v_mfma_f32_32x32x2_f32 v[4:19], v239, v34, v[4:19]
	v_mfma_f32_32x32x2_f32 v[64:79], v238, v34, v[64:79]
	v_add_co_u32_e32 v254, vcc, 0x13000, v120
	s_nop 1
	v_addc_co_u32_e32 v255, vcc, 0, v121, vcc
	global_load_dword v238, v[254:255], off
	global_load_dword v239, v[254:255], off offset:2048
	s_waitcnt vmcnt(16)
	v_mfma_f32_32x32x2_f32 v[4:19], v241, v35, v[4:19]
	v_mfma_f32_32x32x2_f32 v[64:79], v240, v35, v[64:79]
	v_add_co_u32_e32 v254, vcc, 0x18000, v120
	s_nop 1
	v_addc_co_u32_e32 v255, vcc, 0, v121, vcc
	global_load_dword v240, v[254:255], off
	global_load_dword v241, v[254:255], off offset:2048
	s_waitcnt vmcnt(16)
	v_mfma_f32_32x32x2_f32 v[4:19], v245, v36, v[4:19]
	v_mfma_f32_32x32x2_f32 v[64:79], v244, v36, v[64:79]
	v_add_co_u32_e32 v254, vcc, 0x19000, v120
	s_nop 1
	v_addc_co_u32_e32 v255, vcc, 0, v121, vcc
	global_load_dword v244, v[254:255], off
	global_load_dword v245, v[254:255], off offset:2048
	s_waitcnt vmcnt(16)
	v_mfma_f32_32x32x2_f32 v[4:19], v247, v37, v[4:19]
	v_mfma_f32_32x32x2_f32 v[64:79], v246, v37, v[64:79]
	v_add_co_u32_e32 v254, vcc, 0x1a000, v120
	s_nop 1
	v_addc_co_u32_e32 v255, vcc, 0, v121, vcc
	global_load_dword v246, v[254:255], off
	global_load_dword v247, v[254:255], off offset:2048
	s_waitcnt vmcnt(16)
	v_mfma_f32_32x32x2_f32 v[4:19], v249, v38, v[4:19]
	v_mfma_f32_32x32x2_f32 v[64:79], v248, v38, v[64:79]
	v_add_co_u32_e32 v254, vcc, 0x1b000, v120
	s_nop 1
	v_addc_co_u32_e32 v255, vcc, 0, v121, vcc
	global_load_dword v248, v[254:255], off
	global_load_dword v249, v[254:255], off offset:2048
	s_waitcnt vmcnt(16)
	v_mfma_f32_32x32x2_f32 v[4:19], v251, v39, v[4:19]
	v_mfma_f32_32x32x2_f32 v[64:79], v250, v39, v[64:79]
	v_add_co_u32_e32 v254, vcc, 0x20000, v120
	s_nop 1
	v_addc_co_u32_e32 v255, vcc, 0, v121, vcc
	global_load_dword v250, v[254:255], off
	global_load_dword v251, v[254:255], off offset:2048
	s_waitcnt vmcnt(16)
	v_mfma_f32_32x32x2_f32 v[4:19], v253, v40, v[4:19]
	v_mfma_f32_32x32x2_f32 v[64:79], v252, v40, v[64:79]
	v_add_co_u32_e32 v254, vcc, 0x21000, v120
	s_nop 1
	v_addc_co_u32_e32 v255, vcc, 0, v121, vcc
	global_load_dword v252, v[254:255], off
	global_load_dword v253, v[254:255], off offset:2048
	s_waitcnt vmcnt(16)
	v_mfma_f32_32x32x2_f32 v[4:19], v235, v41, v[4:19]
	v_mfma_f32_32x32x2_f32 v[64:79], v234, v41, v[64:79]
	v_add_co_u32_e32 v254, vcc, 0x22000, v120
	s_nop 1
	v_addc_co_u32_e32 v255, vcc, 0, v121, vcc
	global_load_dword v234, v[254:255], off
	global_load_dword v235, v[254:255], off offset:2048
	s_waitcnt vmcnt(16)
	v_mfma_f32_32x32x2_f32 v[4:19], v237, v42, v[4:19]
	v_mfma_f32_32x32x2_f32 v[64:79], v236, v42, v[64:79]
	v_add_co_u32_e32 v254, vcc, 0x23000, v120
	s_nop 1
	v_addc_co_u32_e32 v255, vcc, 0, v121, vcc
	global_load_dword v236, v[254:255], off
	global_load_dword v237, v[254:255], off offset:2048
	s_waitcnt vmcnt(16)
; __device__ __forceinline__ unsigned f2bf(float f) { unsigned u = __builtin_bit_cast(unsigned, f); return (u + 0x7fffu + ((u >> 16) & 1u)) >> 16; }
; __device__ __forceinline__ int crow16(int r, int hi) { return (r & 3) + 8 * (r >> 2) + 4 * hi; }
; __device__ __forceinline__ void filter_item32(const Args& a, int L, bf16* KR, int t0, int np0, int npn, int lane) {
;     ...
; #pragma unroll
;         for (int kk = 0; kk < 32; ++kk) {
;             const float* ub = wr + (32 * (kk >> 4) + crow16(kk & 15, 0)) * 1024;
;             const float zb = kk < 16 ? h0[kk & 15] : h1[kk & 15];
;             const float af = ub[lo4], ab = ub[lo4 + 512];
;             of = __builtin_amdgcn_mfma_f32_32x32x2f32(af, zb, of, 0, 0, 0); ob = __builtin_amdgcn_mfma_f32_32x32x2f32(ab, zb, ob, 0, 0, 0);
;         }
; #pragma unroll
;         for (int r = 0; r < 16; ++r) { const int c = 32 * np + crow16(r, hi); const float ad = -(dmin + (float)c * ((dmax - dmin) / 511.0f));
;             const float dec = expf(-tt * ad); bf16* kr = KR + (size_t)c * (2 * L);
;             if (t == 0) { kr[L] = (bf16)f2bf(of[r] + ob[r]); kr[0] = 0; } else { kr[L - t] = (bf16)f2bf(of[r] * dec); kr[L + t] = (bf16)f2bf(ob[r] * dec); } }
	v_mfma_f32_32x32x2_f32 v[4:19], v239, v43, v[4:19]
	v_mfma_f32_32x32x2_f32 v[64:79], v238, v43, v[64:79]
	v_add_co_u32_e32 v254, vcc, 0x28000, v120
	s_nop 1
	v_addc_co_u32_e32 v255, vcc, 0, v121, vcc
	global_load_dword v238, v[254:255], off
	global_load_dword v239, v[254:255], off offset:2048
	s_waitcnt vmcnt(16)
	v_mfma_f32_32x32x2_f32 v[4:19], v241, v44, v[4:19]
	v_mfma_f32_32x32x2_f32 v[64:79], v240, v44, v[64:79]
	v_add_co_u32_e32 v254, vcc, 0x29000, v120
	s_nop 1
	v_addc_co_u32_e32 v255, vcc, 0, v121, vcc
	global_load_dword v240, v[254:255], off
	global_load_dword v241, v[254:255], off offset:2048
	s_waitcnt vmcnt(16)
	v_mfma_f32_32x32x2_f32 v[4:19], v245, v45, v[4:19]
	v_mfma_f32_32x32x2_f32 v[64:79], v244, v45, v[64:79]
	v_add_co_u32_e32 v254, vcc, 0x2a000, v120
	s_nop 1
	v_addc_co_u32_e32 v255, vcc, 0, v121, vcc
	global_load_dword v244, v[254:255], off
	global_load_dword v245, v[254:255], off offset:2048
	s_waitcnt vmcnt(16)
	v_mfma_f32_32x32x2_f32 v[4:19], v247, v46, v[4:19]
	v_mfma_f32_32x32x2_f32 v[64:79], v246, v46, v[64:79]
	v_add_co_u32_e32 v254, vcc, 0x2b000, v120
	s_nop 1
	v_addc_co_u32_e32 v255, vcc, 0, v121, vcc
	global_load_dword v246, v[254:255], off
	global_load_dword v247, v[254:255], off offset:2048
	s_waitcnt vmcnt(16)
	v_mfma_f32_32x32x2_f32 v[4:19], v249, v47, v[4:19]
	v_mfma_f32_32x32x2_f32 v[64:79], v248, v47, v[64:79]
	v_add_co_u32_e32 v254, vcc, 0x30000, v120
	s_nop 1
	v_addc_co_u32_e32 v255, vcc, 0, v121, vcc
	global_load_dword v248, v[254:255], off
	global_load_dword v249, v[254:255], off offset:2048
	s_waitcnt vmcnt(16)
	v_mfma_f32_32x32x2_f32 v[4:19], v251, v48, v[4:19]
	v_mfma_f32_32x32x2_f32 v[64:79], v250, v48, v[64:79]
	v_add_co_u32_e32 v254, vcc, 0x31000, v120
	s_nop 1
	v_addc_co_u32_e32 v255, vcc, 0, v121, vcc
	global_load_dword v250, v[254:255], off
	global_load_dword v251, v[254:255], off offset:2048
	s_waitcnt vmcnt(16)
	v_mfma_f32_32x32x2_f32 v[4:19], v253, v49, v[4:19]
	v_mfma_f32_32x32x2_f32 v[64:79], v252, v49, v[64:79]
	v_add_co_u32_e32 v254, vcc, 0x32000, v120
	s_nop 1
	v_addc_co_u32_e32 v255, vcc, 0, v121, vcc
	global_load_dword v252, v[254:255], off
	global_load_dword v253, v[254:255], off offset:2048
	s_waitcnt vmcnt(16)
	v_mfma_f32_32x32x2_f32 v[4:19], v235, v50, v[4:19]
	v_mfma_f32_32x32x2_f32 v[64:79], v234, v50, v[64:79]
	v_add_co_u32_e32 v254, vcc, 0x33000, v120
	s_nop 1
	v_addc_co_u32_e32 v255, vcc, 0, v121, vcc
	global_load_dword v234, v[254:255], off
	global_load_dword v235, v[254:255], off offset:2048
	s_waitcnt vmcnt(16)
	v_mfma_f32_32x32x2_f32 v[4:19], v237, v53, v[4:19]
	v_mfma_f32_32x32x2_f32 v[64:79], v236, v53, v[64:79]
	v_add_co_u32_e32 v254, vcc, 0x38000, v120
	s_nop 1
	v_addc_co_u32_e32 v255, vcc, 0, v121, vcc
	global_load_dword v236, v[254:255], off
	global_load_dword v237, v[254:255], off offset:2048
	s_waitcnt vmcnt(16)
	v_mfma_f32_32x32x2_f32 v[4:19], v239, v54, v[4:19]
	v_mfma_f32_32x32x2_f32 v[64:79], v238, v54, v[64:79]
	v_add_co_u32_e32 v254, vcc, 0x39000, v120
	s_nop 1
	v_addc_co_u32_e32 v255, vcc, 0, v121, vcc
	global_load_dword v238, v[254:255], off
	global_load_dword v239, v[254:255], off offset:2048
	s_waitcnt vmcnt(16)
	v_mfma_f32_32x32x2_f32 v[4:19], v241, v57, v[4:19]
	v_mfma_f32_32x32x2_f32 v[64:79], v240, v57, v[64:79]
	v_add_co_u32_e32 v254, vcc, 0x3a000, v120
	s_nop 1
	v_addc_co_u32_e32 v255, vcc, 0, v121, vcc
	global_load_dword v240, v[254:255], off
	global_load_dword v241, v[254:255], off offset:2048
	s_waitcnt vmcnt(16)
	v_mfma_f32_32x32x2_f32 v[4:19], v245, v58, v[4:19]
	v_mfma_f32_32x32x2_f32 v[64:79], v244, v58, v[64:79]
	v_add_co_u32_e32 v254, vcc, 0x3b000, v120
	s_nop 1
	v_addc_co_u32_e32 v255, vcc, 0, v121, vcc
	global_load_dword v244, v[254:255], off
	global_load_dword v245, v[254:255], off offset:2048
	s_waitcnt vmcnt(16)
	v_mfma_f32_32x32x2_f32 v[4:19], v247, v61, v[4:19]
	v_mfma_f32_32x32x2_f32 v[64:79], v246, v61, v[64:79]
	s_waitcnt vmcnt(14)
	v_mfma_f32_32x32x2_f32 v[4:19], v249, v52, v[4:19]
	v_mfma_f32_32x32x2_f32 v[64:79], v248, v52, v[64:79]
	s_waitcnt vmcnt(12)
	v_mfma_f32_32x32x2_f32 v[4:19], v251, v55, v[4:19]
	v_mfma_f32_32x32x2_f32 v[64:79], v250, v55, v[64:79]
	s_waitcnt vmcnt(10)
	v_mfma_f32_32x32x2_f32 v[4:19], v253, v56, v[4:19]
	v_mfma_f32_32x32x2_f32 v[64:79], v252, v56, v[64:79]
	s_waitcnt vmcnt(8)
	v_mfma_f32_32x32x2_f32 v[4:19], v235, v59, v[4:19]
	v_mfma_f32_32x32x2_f32 v[64:79], v234, v59, v[64:79]
	s_waitcnt vmcnt(6)
	v_mfma_f32_32x32x2_f32 v[4:19], v237, v60, v[4:19]
	v_mfma_f32_32x32x2_f32 v[64:79], v236, v60, v[64:79]
	s_waitcnt vmcnt(4)
	v_mfma_f32_32x32x2_f32 v[4:19], v239, v63, v[4:19]
	v_mfma_f32_32x32x2_f32 v[64:79], v238, v63, v[64:79]
	s_waitcnt vmcnt(2)
	v_mfma_f32_32x32x2_f32 v[4:19], v241, v62, v[4:19]
	v_mfma_f32_32x32x2_f32 v[64:79], v240, v62, v[64:79]
	s_waitcnt vmcnt(0)
	v_mfma_f32_32x32x2_f32 v[64:79], v244, v51, v[64:79]
	v_mfma_f32_32x32x2_f32 v[4:19], v245, v51, v[4:19]
	v_lshl_add_u64 v[124:125], s[4:5], 0, v[116:117]
	v_lshl_add_u64 v[122:123], s[4:5], 0, v[118:119]
	s_and_saveexec_b64 s[6:7], s[2:3]
	s_xor_b64 s[6:7], exec, s[6:7]
	s_cbranch_execnz .LBB0_350
	s_or_saveexec_b64 s[6:7], s[6:7]
	v_lshl_add_u64 v[126:127], s[4:5], 0, v[114:115]
	s_xor_b64 exec, exec, s[6:7]
	s_cbranch_execnz .LBB0_351
